# attention item epilogue: l row sums via permlane16/32 swaps instead of ds_bpermute
# speedup vs baseline: 1.0033x; 1.0033x over previous
; DEVI unsigned pk_bf16(float lo, float hi) { unsigned r; asm("v_cvt_pk_bf16_f32 %0, %1, %2" : "=v"(r) : "v"(lo), "v"(hi)); return r; }
; template <int DK, bool BIAS> ...
;     ...
; #pragma unroll
;   for (int qi = 0; qi < 2; ++qi) {
;     const int qg = q0 + 32 * w + 16 * qi + fr;
;     float l = lrun[qi]; l += __shfl_xor(l, 16); l += __shfl_xor(l, 32);
;     const float inv = 1.0f / l;
;     if (qg < qend) {
; #pragma unroll
;       for (int et = 0; et < 4; ++et) { uint2 o; o.x = pk_bf16(O[et][qi][0] * inv, O[et][qi][1] * inv); o.y = pk_bf16(O[et][qi][2] * inv, O[et][qi][3] * inv);
;         *(uint2*)(Op + (size_t)(rowb + qg) * 1024 + 16 * et + 4 * fq) = o; }
;     }
;   }
.LBB0_1801:
	s_mov_b32 s98, 1
	v_readlane_b32 s100, v254, 47
	v_readlane_b32 s101, v254, 48
	v_cmp_eq_u32_e32 vcc, 0, v128
	s_and_saveexec_b64 vcc, vcc
	v_mov_b32_e32 v251, 1
	s_nop 2
	global_atomic_add v251, v130, v251, s[100:101] sc0
	s_mov_b64 exec, vcc
	v_cmp_lt_i32_e32 vcc, v186, v184
	v_readlane_b32 s0, v254, 55
	s_add_u32 s0, s0, s36
	v_cndmask_b32_e32 v0, v183, v186, vcc
	v_lshlrev_b32_e32 v0, 2, v0
	v_mov_b32_e32 v2, v107
	s_nop 1
	v_permlane16_swap_b32_e32 v2, v107
	v_cmp_lt_i32_e32 vcc, v185, v184
	v_readlane_b32 s1, v254, 56
	s_addc_u32 s1, s1, 0
	v_cndmask_b32_e32 v1, v183, v185, vcc
	v_lshlrev_b32_e32 v1, 2, v1
	s_waitcnt lgkmcnt(0)
	v_add_f32_e32 v2, v107, v2
	v_mov_b32_e32 v3, v2
	s_nop 1
	v_permlane32_swap_b32_e32 v3, v2
	v_lshlrev_b32_e32 v4, 1, v103
	v_mov_b32_e32 v5, v130
	v_lshl_add_u64 v[4:5], s[0:1], 0, v[4:5]
	s_and_saveexec_b64 s[0:1], s[4:5]
	s_cbranch_execz .LBB0_1803
	s_waitcnt lgkmcnt(0)
	v_add_f32_e32 v2, v2, v3
	v_div_scale_f32 v3, s[4:5], v2, v2, 1.0
	v_rcp_f32_e32 v6, v3
	v_div_scale_f32 v7, vcc, 1.0, v2, 1.0
	v_fma_f32 v8, -v3, v6, 1.0
	v_fmac_f32_e32 v6, v8, v6
	v_mul_f32_e32 v8, v7, v6
	v_fma_f32 v9, -v3, v8, v7
	v_fmac_f32_e32 v8, v9, v6
	v_fma_f32 v3, -v3, v8, v7
	v_div_fmas_f32 v3, v3, v6, v8
	v_div_fixup_f32 v8, v3, v2, 1.0
	v_mul_f32_e32 v6, v48, v8
	v_mul_f32_e32 v7, v49, v8
	v_lshlrev_b64 v[2:3], 11, v[100:101]
	v_cvt_pk_bf16_f32 v6, v6, v7
	v_mul_f32_e32 v7, v50, v8
	v_lshl_add_u64 v[2:3], v[4:5], 0, v[2:3]
	v_mul_f32_e32 v9, v51, v8
	v_cvt_pk_bf16_f32 v7, v7, v9
	global_store_dwordx2 v[2:3], v[6:7], off
	v_mul_f32_e32 v6, v52, v8
	v_mul_f32_e32 v7, v53, v8
	v_cvt_pk_bf16_f32 v6, v6, v7
	v_mul_f32_e32 v7, v54, v8
	v_mul_f32_e32 v9, v55, v8
	v_cvt_pk_bf16_f32 v7, v7, v9
	global_store_dwordx2 v[2:3], v[6:7], off offset:32
	v_mul_f32_e32 v6, v56, v8
	v_mul_f32_e32 v7, v57, v8
	v_cvt_pk_bf16_f32 v6, v6, v7
	v_mul_f32_e32 v7, v58, v8
	v_mul_f32_e32 v9, v59, v8
	v_cvt_pk_bf16_f32 v7, v7, v9
	global_store_dwordx2 v[2:3], v[6:7], off offset:64
	v_mul_f32_e32 v6, v60, v8
	v_mul_f32_e32 v7, v61, v8
	v_cvt_pk_bf16_f32 v6, v6, v7
	v_mul_f32_e32 v7, v62, v8
	v_mul_f32_e32 v8, v63, v8
	v_cvt_pk_bf16_f32 v7, v7, v8
	global_store_dwordx2 v[2:3], v[6:7], off offset:96
.LBB0_1803:
	s_or_b64 exec, exec, s[0:1]
	v_mov_b32_e32 v0, v106
	s_nop 1
	v_permlane16_swap_b32_e32 v0, v106
	s_mov_b64 s[0:1], 0
	s_mov_b64 s[92:93], 0
	s_waitcnt lgkmcnt(0)
	v_add_f32_e32 v6, v106, v0
	v_mov_b32_e32 v7, v6
	s_nop 1
	v_permlane32_swap_b32_e32 v7, v6
	s_and_saveexec_b64 s[4:5], s[2:3]
	s_xor_b64 s[2:3], exec, s[4:5]
	s_cbranch_execz .LBB0_1805
	s_waitcnt lgkmcnt(0)
	v_add_f32_e32 v0, v6, v7
	v_div_scale_f32 v1, s[4:5], v0, v0, 1.0
	v_rcp_f32_e32 v2, v1
	s_mov_b64 s[92:93], exec
	v_fma_f32 v3, -v1, v2, 1.0
	v_fmac_f32_e32 v2, v3, v2
	v_div_scale_f32 v3, vcc, 1.0, v0, 1.0
	v_mul_f32_e32 v6, v3, v2
	v_fma_f32 v7, -v1, v6, v3
	v_fmac_f32_e32 v6, v7, v2
	v_fma_f32 v1, -v1, v6, v3
	v_div_fmas_f32 v1, v1, v2, v6
	v_div_fixup_f32 v6, v1, v0, 1.0
	v_mul_f32_e32 v2, v44, v6
	v_mul_f32_e32 v3, v45, v6
	v_lshlrev_b64 v[0:1], 11, v[98:99]
	v_cvt_pk_bf16_f32 v2, v2, v3
	v_mul_f32_e32 v3, v46, v6
	v_lshl_add_u64 v[0:1], v[4:5], 0, v[0:1]
	v_mul_f32_e32 v4, v47, v6
	v_cvt_pk_bf16_f32 v3, v3, v4
	global_store_dwordx2 v[0:1], v[2:3], off
	v_mul_f32_e32 v2, v40, v6
	v_mul_f32_e32 v3, v41, v6
	v_cvt_pk_bf16_f32 v2, v2, v3
	v_mul_f32_e32 v3, v42, v6
	v_mul_f32_e32 v4, v43, v6
	v_cvt_pk_bf16_f32 v3, v3, v4
	global_store_dwordx2 v[0:1], v[2:3], off offset:32
	v_mul_f32_e32 v2, v36, v6
	v_mul_f32_e32 v3, v37, v6
	v_cvt_pk_bf16_f32 v2, v2, v3
	v_mul_f32_e32 v3, v38, v6
	v_mul_f32_e32 v4, v39, v6
	v_cvt_pk_bf16_f32 v3, v3, v4
	global_store_dwordx2 v[0:1], v[2:3], off offset:64
	v_mul_f32_e32 v2, v32, v6
	v_mul_f32_e32 v3, v33, v6
	v_cvt_pk_bf16_f32 v2, v2, v3
	v_mul_f32_e32 v3, v34, v6
	v_mul_f32_e32 v4, v35, v6
	v_cvt_pk_bf16_f32 v3, v3, v4

; DEVI unsigned pk_bf16(float lo, float hi) { unsigned r; asm("v_cvt_pk_bf16_f32 %0, %1, %2" : "=v"(r) : "v"(lo), "v"(hi)); return r; }
; template <int DK, bool BIAS> ...
;     ...
; #pragma unroll
;   for (int qi = 0; qi < 2; ++qi) {
;     const int qg = q0 + 32 * w + 16 * qi + fr;
;     float l = lrun[qi]; l += __shfl_xor(l, 16); l += __shfl_xor(l, 32);
;     const float inv = 1.0f / l;
;     if (qg < qend) {
; #pragma unroll
;       for (int et = 0; et < 4; ++et) { uint2 o; o.x = pk_bf16(O[et][qi][0] * inv, O[et][qi][1] * inv); o.y = pk_bf16(O[et][qi][2] * inv, O[et][qi][3] * inv);
;         *(uint2*)(Op + (size_t)(rowb + qg) * 1024 + 16 * et + 4 * fq) = o; }
;     }
;   }
.LBB0_1891:
	s_mov_b32 s98, 1
	v_readlane_b32 s100, v254, 47
	v_readlane_b32 s101, v254, 48
	v_cmp_eq_u32_e32 vcc, 0, v128
	s_and_saveexec_b64 vcc, vcc
	v_mov_b32_e32 v251, 1
	s_nop 2
	global_atomic_add v251, v130, v251, s[100:101] sc0
	s_mov_b64 exec, vcc
	v_cmp_lt_i32_e32 vcc, v186, v184
	s_lshl_b32 s0, s20, 7
	v_readlane_b32 s6, v254, 18
	v_cndmask_b32_e32 v0, v183, v186, vcc
	v_lshlrev_b32_e32 v0, 2, v0
	v_mov_b32_e32 v2, v121
	s_nop 1
	v_permlane16_swap_b32_e32 v2, v121
	v_cmp_lt_i32_e32 vcc, v185, v184
	v_readlane_b32 s7, v254, 19
	s_add_u32 s0, s6, s0
	v_cndmask_b32_e32 v1, v183, v185, vcc
	v_lshlrev_b32_e32 v1, 2, v1
	s_waitcnt lgkmcnt(0)
	v_add_f32_e32 v2, v121, v2
	v_mov_b32_e32 v3, v2
	s_nop 1
	v_permlane32_swap_b32_e32 v3, v2
	s_addc_u32 s1, s7, 0
	v_lshlrev_b32_e32 v4, 1, v200
	v_mov_b32_e32 v5, v130
	v_lshl_add_u64 v[4:5], s[0:1], 0, v[4:5]
	s_and_saveexec_b64 s[0:1], s[2:3]
	s_cbranch_execz .LBB0_1893
	s_waitcnt lgkmcnt(0)
	v_add_f32_e32 v2, v2, v3
	v_div_scale_f32 v3, s[2:3], v2, v2, 1.0
	v_rcp_f32_e32 v6, v3
	v_div_scale_f32 v7, vcc, 1.0, v2, 1.0
	v_fma_f32 v8, -v3, v6, 1.0
	v_fmac_f32_e32 v6, v8, v6
	v_mul_f32_e32 v8, v7, v6
	v_fma_f32 v9, -v3, v8, v7
	v_fmac_f32_e32 v8, v9, v6
	v_fma_f32 v3, -v3, v8, v7
	v_div_fmas_f32 v3, v3, v6, v8
	v_div_fixup_f32 v8, v3, v2, 1.0
	v_mul_f32_e32 v6, v64, v8
	v_mul_f32_e32 v7, v65, v8
	v_lshlrev_b64 v[2:3], 11, v[112:113]
	v_cvt_pk_bf16_f32 v6, v6, v7
	v_mul_f32_e32 v7, v66, v8
	v_lshl_add_u64 v[2:3], v[4:5], 0, v[2:3]
	v_mul_f32_e32 v9, v67, v8
	v_cvt_pk_bf16_f32 v7, v7, v9
	global_store_dwordx2 v[2:3], v[6:7], off
	v_mul_f32_e32 v6, v68, v8
	v_mul_f32_e32 v7, v69, v8
	v_cvt_pk_bf16_f32 v6, v6, v7
	v_mul_f32_e32 v7, v70, v8
	v_mul_f32_e32 v9, v71, v8
	v_cvt_pk_bf16_f32 v7, v7, v9
	global_store_dwordx2 v[2:3], v[6:7], off offset:32
	v_mul_f32_e32 v6, v72, v8
	v_mul_f32_e32 v7, v73, v8
	v_cvt_pk_bf16_f32 v6, v6, v7
	v_mul_f32_e32 v7, v74, v8
	v_mul_f32_e32 v9, v75, v8
	v_cvt_pk_bf16_f32 v7, v7, v9
	global_store_dwordx2 v[2:3], v[6:7], off offset:64
	v_mul_f32_e32 v6, v76, v8
	v_mul_f32_e32 v7, v77, v8
	v_cvt_pk_bf16_f32 v6, v6, v7
	v_mul_f32_e32 v7, v78, v8
	v_mul_f32_e32 v8, v79, v8
	v_cvt_pk_bf16_f32 v7, v7, v8
	global_store_dwordx2 v[2:3], v[6:7], off offset:96
.LBB0_1893:
	s_or_b64 exec, exec, s[0:1]
	v_mov_b32_e32 v0, v120
	s_nop 1
	v_permlane16_swap_b32_e32 v0, v120
	s_waitcnt lgkmcnt(0)
	v_add_f32_e32 v6, v120, v0
	v_mov_b32_e32 v7, v6
	s_nop 1
	v_permlane32_swap_b32_e32 v7, v6
	s_and_saveexec_b64 s[0:1], s[4:5]
	v_readlane_b32 s58, v255, 13
	s_cbranch_execz .LBB0_1895
	s_waitcnt lgkmcnt(0)
	v_add_f32_e32 v0, v6, v7
	v_div_scale_f32 v1, s[2:3], v0, v0, 1.0
	v_rcp_f32_e32 v2, v1
	v_div_scale_f32 v3, vcc, 1.0, v0, 1.0
	s_or_b64 s[92:93], s[92:93], exec
	v_fma_f32 v6, -v1, v2, 1.0
	v_fmac_f32_e32 v2, v6, v2
	v_mul_f32_e32 v6, v3, v2
	v_fma_f32 v7, -v1, v6, v3
	v_fmac_f32_e32 v6, v7, v2
	v_fma_f32 v1, -v1, v6, v3
	v_div_fmas_f32 v1, v1, v2, v6
	v_div_fixup_f32 v6, v1, v0, 1.0
	v_mul_f32_e32 v2, v48, v6
	v_mul_f32_e32 v3, v49, v6
	v_lshlrev_b64 v[0:1], 11, v[114:115]
	v_cvt_pk_bf16_f32 v2, v2, v3
	v_mul_f32_e32 v3, v50, v6
	v_lshl_add_u64 v[0:1], v[4:5], 0, v[0:1]
	v_mul_f32_e32 v4, v51, v6
	v_cvt_pk_bf16_f32 v3, v3, v4
	global_store_dwordx2 v[0:1], v[2:3], off
	v_mul_f32_e32 v2, v52, v6
	v_mul_f32_e32 v3, v53, v6
	v_cvt_pk_bf16_f32 v2, v2, v3
	v_mul_f32_e32 v3, v54, v6
	v_mul_f32_e32 v4, v55, v6
	v_cvt_pk_bf16_f32 v3, v3, v4
	global_store_dwordx2 v[0:1], v[2:3], off offset:32
	v_mul_f32_e32 v2, v56, v6
	v_mul_f32_e32 v3, v57, v6
	v_cvt_pk_bf16_f32 v2, v2, v3
	v_mul_f32_e32 v3, v58, v6
	v_mul_f32_e32 v4, v59, v6
	v_cvt_pk_bf16_f32 v3, v3, v4
	global_store_dwordx2 v[0:1], v[2:3], off offset:64
	v_mul_f32_e32 v2, v60, v6
	v_mul_f32_e32 v3, v61, v6
	v_cvt_pk_bf16_f32 v2, v2, v3
	v_mul_f32_e32 v3, v62, v6
	v_mul_f32_e32 v4, v63, v6
	v_cvt_pk_bf16_f32 v3, v3, v4
